# G6 epilogue: residual rows of the third row block prefetched at the start of the last K-tile (into the unused accumulator registers), one fewer exposed load wait
# baseline (speedup 1.0000x reference)
.LBB0_224:
	s_or_b64 exec, exec, s[0:1]
	v_add_u32_e32 v222, v170, v168
	v_or_b32_e32 v223, v169, v167
	v_lshlrev_b32_e32 v221, 12, v222
	v_lshl_add_u32 v221, v223, 2, v221
	s_mov_b32 s0, s68
	s_mov_b32 s1, s69
	global_load_dword v189, v221, s[0:1]
	global_load_dword v205, v221, s[0:1] offset:128
	s_add_u32 s0, s68, 0x1000
	s_addc_u32 s1, s69, 0
	global_load_dword v190, v221, s[0:1]
	global_load_dword v206, v221, s[0:1] offset:128
	s_add_u32 s0, s68, 0x2000
	s_addc_u32 s1, s69, 0
	global_load_dword v191, v221, s[0:1]
	global_load_dword v207, v221, s[0:1] offset:128
	s_add_u32 s0, s68, 0x3000
	s_addc_u32 s1, s69, 0
	global_load_dword v192, v221, s[0:1]
	global_load_dword v208, v221, s[0:1] offset:128
	s_add_u32 s0, s68, 0x8000
	s_addc_u32 s1, s69, 0
	global_load_dword v193, v221, s[0:1]
	global_load_dword v209, v221, s[0:1] offset:128
	s_add_u32 s0, s68, 0x9000
	s_addc_u32 s1, s69, 0
	global_load_dword v194, v221, s[0:1]
	global_load_dword v210, v221, s[0:1] offset:128
	s_add_u32 s0, s68, 0xa000
	s_addc_u32 s1, s69, 0
	global_load_dword v195, v221, s[0:1]
	global_load_dword v211, v221, s[0:1] offset:128
	s_add_u32 s0, s68, 0xb000
	s_addc_u32 s1, s69, 0
	global_load_dword v196, v221, s[0:1]
	global_load_dword v212, v221, s[0:1] offset:128
	s_add_u32 s0, s68, 0x10000
	s_addc_u32 s1, s69, 0
	global_load_dword v197, v221, s[0:1]
	global_load_dword v213, v221, s[0:1] offset:128
	s_add_u32 s0, s68, 0x11000
	s_addc_u32 s1, s69, 0
	global_load_dword v198, v221, s[0:1]
	global_load_dword v214, v221, s[0:1] offset:128
	s_add_u32 s0, s68, 0x12000
	s_addc_u32 s1, s69, 0
	global_load_dword v199, v221, s[0:1]
	global_load_dword v215, v221, s[0:1] offset:128
	s_add_u32 s0, s68, 0x13000
	s_addc_u32 s1, s69, 0
	global_load_dword v200, v221, s[0:1]
	global_load_dword v216, v221, s[0:1] offset:128
	s_add_u32 s0, s68, 0x18000
	s_addc_u32 s1, s69, 0
	global_load_dword v201, v221, s[0:1]
	global_load_dword v217, v221, s[0:1] offset:128
	s_add_u32 s0, s68, 0x19000
	s_addc_u32 s1, s69, 0
	global_load_dword v202, v221, s[0:1]
	global_load_dword v218, v221, s[0:1] offset:128
	s_add_u32 s0, s68, 0x1a000
	s_addc_u32 s1, s69, 0
	global_load_dword v203, v221, s[0:1]
	global_load_dword v219, v221, s[0:1] offset:128
	s_add_u32 s0, s68, 0x1b000
	s_addc_u32 s1, s69, 0
	global_load_dword v204, v221, s[0:1]
	global_load_dword v220, v221, s[0:1] offset:128
	v_add_u32_e32 v131, v130, v172
	ds_read_b128 v[132:135], v131
	ds_read_b128 v[136:139], v131 offset:4096
	ds_read_b128 v[140:143], v131 offset:8192
	v_add_u32_e32 v131, v128, v172
	ds_read_b128 v[154:157], v131 offset:32768
	ds_read_b128 v[158:161], v131 offset:36864
	s_setprio 1
	s_waitcnt lgkmcnt(0)
	v_mfma_f32_32x32x16_bf16 v[112:127], v[132:135], v[154:157], v[112:127]
	v_mfma_f32_32x32x16_bf16 v[96:111], v[132:135], v[158:161], v[96:111]
	v_mfma_f32_32x32x16_bf16 v[80:95], v[136:139], v[154:157], v[80:95]
	v_mfma_f32_32x32x16_bf16 v[64:79], v[136:139], v[158:161], v[64:79]
	v_mfma_f32_32x32x16_bf16 v[48:63], v[140:143], v[154:157], v[48:63]
	v_mfma_f32_32x32x16_bf16 v[32:47], v[140:143], v[158:161], v[32:47]
	s_setprio 0
	v_add_u32_e32 v142, v130, v171
	ds_read_b128 v[130:133], v142
	ds_read_b128 v[134:137], v142 offset:4096
	ds_read_b128 v[138:141], v142 offset:8192
	v_add_u32_e32 v128, v128, v171
	ds_read_b128 v[150:153], v128 offset:32768
	ds_read_b128 v[154:157], v128 offset:36864
	s_setprio 1
	s_waitcnt lgkmcnt(0)
	v_mfma_f32_32x32x16_bf16 v[112:127], v[130:133], v[150:153], v[112:127]
	v_mfma_f32_32x32x16_bf16 v[96:111], v[130:133], v[154:157], v[96:111]
	v_mfma_f32_32x32x16_bf16 v[80:95], v[134:137], v[150:153], v[80:95]
	v_mfma_f32_32x32x16_bf16 v[64:79], v[134:137], v[154:157], v[64:79]
	v_mfma_f32_32x32x16_bf16 v[48:63], v[138:141], v[150:153], v[48:63]
	v_mfma_f32_32x32x16_bf16 v[32:47], v[138:141], v[154:157], v[32:47]
	s_setprio 0
	v_or_b32_e32 v134, v169, v167
	v_readlane_b32 s1, v254, 62
	s_movk_i32 s0, 0x6000
	v_lshlrev_b32_e32 v134, 2, v134
	v_add_u32_e32 v222, v170, v168
	v_add_u32_e32 v134, 0x5000, v134
	v_mov_b32_e32 v135, 0
	v_add_u32_e32 v132, 0xffffe000, v222
	v_ashrrev_i32_e32 v132, 10, v132
	v_add_u32_e32 v132, 1, v132
	v_max_i32_e32 v132, 0, v132
	v_add_u32_e32 v132, s1, v132
	v_mov_b64_e32 v[130:131], s[66:67]
	v_mad_u64_u32 v[130:131], vcc, v132, s0, v[130:131]
	v_lshl_add_u64 v[130:131], v[130:131], 0, v[134:135]
	global_load_dword v128, v[130:131], off
	global_load_dword v133, v[130:131], off offset:128
	v_add_u32_e32 v132, 0xffffe020, v222
	v_ashrrev_i32_e32 v132, 10, v132
	v_add_u32_e32 v132, 1, v132
	v_max_i32_e32 v132, 0, v132
	v_add_u32_e32 v132, s1, v132
	v_mov_b64_e32 v[130:131], s[66:67]
	v_mad_u64_u32 v[130:131], vcc, v132, s0, v[130:131]
	v_lshl_add_u64 v[130:131], v[130:131], 0, v[134:135]
	global_load_dword v142, v[130:131], off
	global_load_dword v143, v[130:131], off offset:128
	v_add_u32_e32 v132, 0xffffe040, v222
	v_ashrrev_i32_e32 v132, 10, v132
	v_add_u32_e32 v132, 1, v132
	v_max_i32_e32 v132, 0, v132
	v_add_u32_e32 v132, s1, v132
	v_mov_b64_e32 v[130:131], s[66:67]
	v_mad_u64_u32 v[130:131], vcc, v132, s0, v[130:131]
	v_lshl_add_u64 v[130:131], v[130:131], 0, v[134:135]
	global_load_dword v144, v[130:131], off
	global_load_dword v145, v[130:131], off offset:128
	s_add_u32 s0, s68, 0x20000
	s_addc_u32 s1, s69, 0
	global_load_dword v150, v221, s[0:1]
	global_load_dword v172, v221, s[0:1] offset:128
	s_add_u32 s0, s68, 0x21000
	s_addc_u32 s1, s69, 0
	global_load_dword v151, v221, s[0:1]
	global_load_dword v173, v221, s[0:1] offset:128
	s_add_u32 s0, s68, 0x22000
	s_addc_u32 s1, s69, 0
	global_load_dword v152, v221, s[0:1]
	global_load_dword v174, v221, s[0:1] offset:128
	s_add_u32 s0, s68, 0x23000
	s_addc_u32 s1, s69, 0
	global_load_dword v153, v221, s[0:1]
	global_load_dword v175, v221, s[0:1] offset:128
	s_add_u32 s0, s68, 0x28000
	s_addc_u32 s1, s69, 0
	global_load_dword v154, v221, s[0:1]
	global_load_dword v176, v221, s[0:1] offset:128
	s_add_u32 s0, s68, 0x29000
	s_addc_u32 s1, s69, 0
	global_load_dword v155, v221, s[0:1]
	global_load_dword v177, v221, s[0:1] offset:128
	s_add_u32 s0, s68, 0x2a000
	s_addc_u32 s1, s69, 0
	global_load_dword v156, v221, s[0:1]
	global_load_dword v178, v221, s[0:1] offset:128
	s_add_u32 s0, s68, 0x2b000
	s_addc_u32 s1, s69, 0
	global_load_dword v157, v221, s[0:1]
	global_load_dword v179, v221, s[0:1] offset:128
	s_add_u32 s0, s68, 0x30000
	s_addc_u32 s1, s69, 0
	global_load_dword v158, v221, s[0:1]
	global_load_dword v180, v221, s[0:1] offset:128
	s_add_u32 s0, s68, 0x31000
	s_addc_u32 s1, s69, 0
	global_load_dword v159, v221, s[0:1]
	global_load_dword v181, v221, s[0:1] offset:128
	s_add_u32 s0, s68, 0x32000
	s_addc_u32 s1, s69, 0
	global_load_dword v160, v221, s[0:1]
	global_load_dword v182, v221, s[0:1] offset:128
	s_add_u32 s0, s68, 0x33000
	s_addc_u32 s1, s69, 0
	global_load_dword v161, v221, s[0:1]
	global_load_dword v183, v221, s[0:1] offset:128
	s_add_u32 s0, s68, 0x38000
	s_addc_u32 s1, s69, 0
	global_load_dword v162, v221, s[0:1]
	global_load_dword v184, v221, s[0:1] offset:128
	s_add_u32 s0, s68, 0x39000
	s_addc_u32 s1, s69, 0
	global_load_dword v163, v221, s[0:1]
	global_load_dword v185, v221, s[0:1] offset:128
	s_add_u32 s0, s68, 0x3a000
	s_addc_u32 s1, s69, 0
	global_load_dword v164, v221, s[0:1]
	global_load_dword v186, v221, s[0:1] offset:128
	s_add_u32 s0, s68, 0x3b000
	s_addc_u32 s1, s69, 0
	global_load_dword v165, v221, s[0:1]
	global_load_dword v187, v221, s[0:1] offset:128
	s_waitcnt vmcnt(32)
	v_fmac_f32_e32 v189, v112, v128
	v_fmac_f32_e32 v190, v113, v128
	v_fmac_f32_e32 v191, v114, v128
	v_fmac_f32_e32 v192, v115, v128
	v_fmac_f32_e32 v193, v116, v128
	v_fmac_f32_e32 v194, v117, v128
	v_fmac_f32_e32 v195, v118, v128
	v_fmac_f32_e32 v196, v119, v128
	v_fmac_f32_e32 v197, v120, v128
	v_fmac_f32_e32 v198, v121, v128
	v_fmac_f32_e32 v199, v122, v128
	v_fmac_f32_e32 v200, v123, v128
	v_fmac_f32_e32 v201, v124, v128
	v_fmac_f32_e32 v202, v125, v128
	v_fmac_f32_e32 v203, v126, v128
	v_fmac_f32_e32 v204, v127, v128
	v_fmac_f32_e32 v205, v96, v133
	v_fmac_f32_e32 v206, v97, v133
	v_fmac_f32_e32 v207, v98, v133
	v_fmac_f32_e32 v208, v99, v133
	v_fmac_f32_e32 v209, v100, v133
	v_fmac_f32_e32 v210, v101, v133
	v_fmac_f32_e32 v211, v102, v133
	v_fmac_f32_e32 v212, v103, v133
	v_fmac_f32_e32 v213, v104, v133
	v_fmac_f32_e32 v214, v105, v133
	v_fmac_f32_e32 v215, v106, v133
	v_fmac_f32_e32 v216, v107, v133
	v_fmac_f32_e32 v217, v108, v133
	v_fmac_f32_e32 v218, v109, v133
	v_fmac_f32_e32 v219, v110, v133
	v_fmac_f32_e32 v220, v111, v133
	v_fmac_f32_e32 v0, v48, v144
	v_fmac_f32_e32 v1, v49, v144
	v_fmac_f32_e32 v2, v50, v144
	v_fmac_f32_e32 v3, v51, v144
	v_fmac_f32_e32 v4, v52, v144
	v_fmac_f32_e32 v5, v53, v144
	v_fmac_f32_e32 v6, v54, v144
	v_fmac_f32_e32 v7, v55, v144
	v_fmac_f32_e32 v8, v56, v144
	v_fmac_f32_e32 v9, v57, v144
	v_fmac_f32_e32 v10, v58, v144
	v_fmac_f32_e32 v11, v59, v144
	v_fmac_f32_e32 v12, v60, v144
	v_fmac_f32_e32 v13, v61, v144
	v_fmac_f32_e32 v14, v62, v144
	v_fmac_f32_e32 v15, v63, v144
	v_fmac_f32_e32 v16, v32, v145
	v_fmac_f32_e32 v17, v33, v145
	v_fmac_f32_e32 v18, v34, v145
	v_fmac_f32_e32 v19, v35, v145
	v_fmac_f32_e32 v20, v36, v145
	v_fmac_f32_e32 v21, v37, v145
	v_fmac_f32_e32 v22, v38, v145
	v_fmac_f32_e32 v23, v39, v145
	v_fmac_f32_e32 v24, v40, v145
	v_fmac_f32_e32 v25, v41, v145
	v_fmac_f32_e32 v26, v42, v145
	v_fmac_f32_e32 v27, v43, v145
	v_fmac_f32_e32 v28, v44, v145
	v_fmac_f32_e32 v29, v45, v145
	v_fmac_f32_e32 v30, v46, v145
	v_fmac_f32_e32 v31, v47, v145
	s_waitcnt vmcnt(0)
	v_fmac_f32_e32 v150, v80, v142
	v_fmac_f32_e32 v151, v81, v142
	v_fmac_f32_e32 v152, v82, v142
	v_fmac_f32_e32 v153, v83, v142
	v_fmac_f32_e32 v154, v84, v142
	v_fmac_f32_e32 v155, v85, v142
	v_fmac_f32_e32 v156, v86, v142
	v_fmac_f32_e32 v157, v87, v142
	v_fmac_f32_e32 v158, v88, v142
	v_fmac_f32_e32 v159, v89, v142
	v_fmac_f32_e32 v160, v90, v142
	v_fmac_f32_e32 v161, v91, v142
	v_fmac_f32_e32 v162, v92, v142
	v_fmac_f32_e32 v163, v93, v142
	v_fmac_f32_e32 v164, v94, v142
	v_fmac_f32_e32 v165, v95, v142
	v_fmac_f32_e32 v172, v64, v143
	v_fmac_f32_e32 v173, v65, v143
	v_fmac_f32_e32 v174, v66, v143
	v_fmac_f32_e32 v175, v67, v143
	v_fmac_f32_e32 v176, v68, v143
	v_fmac_f32_e32 v177, v69, v143
	v_fmac_f32_e32 v178, v70, v143
	v_fmac_f32_e32 v179, v71, v143
	v_fmac_f32_e32 v180, v72, v143
	v_fmac_f32_e32 v181, v73, v143
	v_fmac_f32_e32 v182, v74, v143
	v_fmac_f32_e32 v183, v75, v143
	v_fmac_f32_e32 v184, v76, v143
	v_fmac_f32_e32 v185, v77, v143
	v_fmac_f32_e32 v186, v78, v143
	v_fmac_f32_e32 v187, v79, v143
	s_mov_b32 s0, s68
	s_mov_b32 s1, s69
	global_store_dword v221, v189, s[0:1]
	global_store_dword v221, v205, s[0:1] offset:128
	s_add_u32 s0, s68, 0x1000
	s_addc_u32 s1, s69, 0
	global_store_dword v221, v190, s[0:1]
	global_store_dword v221, v206, s[0:1] offset:128
	s_add_u32 s0, s68, 0x2000
	s_addc_u32 s1, s69, 0
	global_store_dword v221, v191, s[0:1]
	global_store_dword v221, v207, s[0:1] offset:128
	s_add_u32 s0, s68, 0x3000
	s_addc_u32 s1, s69, 0
	global_store_dword v221, v192, s[0:1]
	global_store_dword v221, v208, s[0:1] offset:128
	s_add_u32 s0, s68, 0x8000
	s_addc_u32 s1, s69, 0
	global_store_dword v221, v193, s[0:1]
	global_store_dword v221, v209, s[0:1] offset:128
	s_add_u32 s0, s68, 0x9000
	s_addc_u32 s1, s69, 0
	global_store_dword v221, v194, s[0:1]
	global_store_dword v221, v210, s[0:1] offset:128
	s_add_u32 s0, s68, 0xa000
	s_addc_u32 s1, s69, 0
	global_store_dword v221, v195, s[0:1]
	global_store_dword v221, v211, s[0:1] offset:128
	s_add_u32 s0, s68, 0xb000
	s_addc_u32 s1, s69, 0
	global_store_dword v221, v196, s[0:1]
	global_store_dword v221, v212, s[0:1] offset:128
	s_add_u32 s0, s68, 0x10000
	s_addc_u32 s1, s69, 0
	global_store_dword v221, v197, s[0:1]
	global_store_dword v221, v213, s[0:1] offset:128
	s_add_u32 s0, s68, 0x11000
	s_addc_u32 s1, s69, 0
	global_store_dword v221, v198, s[0:1]
	global_store_dword v221, v214, s[0:1] offset:128
	s_add_u32 s0, s68, 0x12000
	s_addc_u32 s1, s69, 0
	global_store_dword v221, v199, s[0:1]
	global_store_dword v221, v215, s[0:1] offset:128
	s_add_u32 s0, s68, 0x13000
	s_addc_u32 s1, s69, 0
	global_store_dword v221, v200, s[0:1]
	global_store_dword v221, v216, s[0:1] offset:128
	s_add_u32 s0, s68, 0x18000
	s_addc_u32 s1, s69, 0
	global_store_dword v221, v201, s[0:1]
	global_store_dword v221, v217, s[0:1] offset:128
	s_add_u32 s0, s68, 0x19000
	s_addc_u32 s1, s69, 0
	global_store_dword v221, v202, s[0:1]
	global_store_dword v221, v218, s[0:1] offset:128
	s_add_u32 s0, s68, 0x1a000
	s_addc_u32 s1, s69, 0
	global_store_dword v221, v203, s[0:1]
	global_store_dword v221, v219, s[0:1] offset:128
	s_add_u32 s0, s68, 0x1b000
	s_addc_u32 s1, s69, 0
	global_store_dword v221, v204, s[0:1]
	global_store_dword v221, v220, s[0:1] offset:128
	s_add_u32 s0, s68, 0x20000
	s_addc_u32 s1, s69, 0
	global_store_dword v221, v150, s[0:1]
	global_store_dword v221, v172, s[0:1] offset:128
	s_add_u32 s0, s68, 0x21000
	s_addc_u32 s1, s69, 0
	global_store_dword v221, v151, s[0:1]
	global_store_dword v221, v173, s[0:1] offset:128
	s_add_u32 s0, s68, 0x22000
	s_addc_u32 s1, s69, 0
	global_store_dword v221, v152, s[0:1]
	global_store_dword v221, v174, s[0:1] offset:128
	s_add_u32 s0, s68, 0x23000
	s_addc_u32 s1, s69, 0
	global_store_dword v221, v153, s[0:1]
	global_store_dword v221, v175, s[0:1] offset:128
	s_add_u32 s0, s68, 0x28000
	s_addc_u32 s1, s69, 0
	global_store_dword v221, v154, s[0:1]
	global_store_dword v221, v176, s[0:1] offset:128
	s_add_u32 s0, s68, 0x29000
	s_addc_u32 s1, s69, 0
	global_store_dword v221, v155, s[0:1]
	global_store_dword v221, v177, s[0:1] offset:128
	s_add_u32 s0, s68, 0x2a000
	s_addc_u32 s1, s69, 0
	global_store_dword v221, v156, s[0:1]
	global_store_dword v221, v178, s[0:1] offset:128
	s_add_u32 s0, s68, 0x2b000
	s_addc_u32 s1, s69, 0
	global_store_dword v221, v157, s[0:1]
	global_store_dword v221, v179, s[0:1] offset:128
	s_add_u32 s0, s68, 0x30000
	s_addc_u32 s1, s69, 0
	global_store_dword v221, v158, s[0:1]
	global_store_dword v221, v180, s[0:1] offset:128
	s_add_u32 s0, s68, 0x31000
	s_addc_u32 s1, s69, 0
	global_store_dword v221, v159, s[0:1]
	global_store_dword v221, v181, s[0:1] offset:128
	s_add_u32 s0, s68, 0x32000
	s_addc_u32 s1, s69, 0
	global_store_dword v221, v160, s[0:1]
	global_store_dword v221, v182, s[0:1] offset:128
	s_add_u32 s0, s68, 0x33000
	s_addc_u32 s1, s69, 0
	global_store_dword v221, v161, s[0:1]
	global_store_dword v221, v183, s[0:1] offset:128
	s_add_u32 s0, s68, 0x38000
	s_addc_u32 s1, s69, 0
	global_store_dword v221, v162, s[0:1]
	global_store_dword v221, v184, s[0:1] offset:128
	s_add_u32 s0, s68, 0x39000
	s_addc_u32 s1, s69, 0
	global_store_dword v221, v163, s[0:1]
	global_store_dword v221, v185, s[0:1] offset:128
	s_add_u32 s0, s68, 0x3a000
	s_addc_u32 s1, s69, 0
	global_store_dword v221, v164, s[0:1]
	global_store_dword v221, v186, s[0:1] offset:128
	s_add_u32 s0, s68, 0x3b000
	s_addc_u32 s1, s69, 0
	global_store_dword v221, v165, s[0:1]
	global_store_dword v221, v187, s[0:1] offset:128
	s_add_u32 s0, s68, 0x40000
	s_addc_u32 s1, s69, 0
	global_store_dword v221, v0, s[0:1]
	global_store_dword v221, v16, s[0:1] offset:128
	s_add_u32 s0, s68, 0x41000
	s_addc_u32 s1, s69, 0
	global_store_dword v221, v1, s[0:1]
	global_store_dword v221, v17, s[0:1] offset:128
	s_add_u32 s0, s68, 0x42000
	s_addc_u32 s1, s69, 0
	global_store_dword v221, v2, s[0:1]
	global_store_dword v221, v18, s[0:1] offset:128
	s_add_u32 s0, s68, 0x43000
	s_addc_u32 s1, s69, 0
	global_store_dword v221, v3, s[0:1]
	global_store_dword v221, v19, s[0:1] offset:128
	s_add_u32 s0, s68, 0x48000
	s_addc_u32 s1, s69, 0
	global_store_dword v221, v4, s[0:1]
	global_store_dword v221, v20, s[0:1] offset:128
	s_add_u32 s0, s68, 0x49000
	s_addc_u32 s1, s69, 0
	global_store_dword v221, v5, s[0:1]
	global_store_dword v221, v21, s[0:1] offset:128
	s_add_u32 s0, s68, 0x4a000
	s_addc_u32 s1, s69, 0
	global_store_dword v221, v6, s[0:1]
	global_store_dword v221, v22, s[0:1] offset:128
	s_add_u32 s0, s68, 0x4b000
	s_addc_u32 s1, s69, 0
	global_store_dword v221, v7, s[0:1]
	global_store_dword v221, v23, s[0:1] offset:128
	s_add_u32 s0, s68, 0x50000
	s_addc_u32 s1, s69, 0
	global_store_dword v221, v8, s[0:1]
	global_store_dword v221, v24, s[0:1] offset:128
	s_add_u32 s0, s68, 0x51000
	s_addc_u32 s1, s69, 0
	global_store_dword v221, v9, s[0:1]
	global_store_dword v221, v25, s[0:1] offset:128
	s_add_u32 s0, s68, 0x52000
	s_addc_u32 s1, s69, 0
	global_store_dword v221, v10, s[0:1]
	global_store_dword v221, v26, s[0:1] offset:128
	s_add_u32 s0, s68, 0x53000
	s_addc_u32 s1, s69, 0
	global_store_dword v221, v11, s[0:1]
	global_store_dword v221, v27, s[0:1] offset:128
	s_add_u32 s0, s68, 0x58000
	s_addc_u32 s1, s69, 0
	global_store_dword v221, v12, s[0:1]
	global_store_dword v221, v28, s[0:1] offset:128
	s_add_u32 s0, s68, 0x59000
	s_addc_u32 s1, s69, 0
	global_store_dword v221, v13, s[0:1]
	global_store_dword v221, v29, s[0:1] offset:128
	s_add_u32 s0, s68, 0x5a000
	s_addc_u32 s1, s69, 0
	global_store_dword v221, v14, s[0:1]
	global_store_dword v221, v30, s[0:1] offset:128
	s_add_u32 s0, s68, 0x5b000
	s_addc_u32 s1, s69, 0
	global_store_dword v221, v15, s[0:1]
	global_store_dword v221, v31, s[0:1] offset:128
	s_andn2_b64 exec, exec, s[46:47]
	s_cbranch_execz .LBB0_237

.LBB0_230:
	s_or_b64 exec, exec, s[6:7]
	v_add_u32_e32 v133, v131, v172
	ds_read_b128 v[190:193], v133
	ds_read_b128 v[194:197], v133 offset:4096
	ds_read_b128 v[198:201], v133 offset:8192
	v_add_u32_e32 v133, v130, v172
	ds_read_b128 v[206:209], v133 offset:32768
	ds_read_b128 v[210:213], v133 offset:36864
	s_setprio 1
	s_waitcnt lgkmcnt(0)
	v_mfma_f32_32x32x16_bf16 v[112:127], v[190:193], v[206:209], v[112:127]
	v_mfma_f32_32x32x16_bf16 v[96:111], v[190:193], v[210:213], v[96:111]
	v_mfma_f32_32x32x16_bf16 v[80:95], v[194:197], v[206:209], v[80:95]
	v_mfma_f32_32x32x16_bf16 v[64:79], v[194:197], v[210:213], v[64:79]
	v_mfma_f32_32x32x16_bf16 v[48:63], v[198:201], v[206:209], v[48:63]
	v_mfma_f32_32x32x16_bf16 v[32:47], v[198:201], v[210:213], v[32:47]
	s_setprio 0
	v_add_u32_e32 v131, v131, v171
	ds_read_b128 v[190:193], v131
	ds_read_b128 v[194:197], v131 offset:4096
	ds_read_b128 v[198:201], v131 offset:8192
	v_add_u32_e32 v130, v130, v171
	ds_read_b128 v[206:209], v130 offset:32768
	ds_read_b128 v[210:213], v130 offset:36864
	s_setprio 1
	s_waitcnt lgkmcnt(0)
	v_mfma_f32_32x32x16_bf16 v[112:127], v[190:193], v[206:209], v[112:127]
	v_mfma_f32_32x32x16_bf16 v[96:111], v[190:193], v[210:213], v[96:111]
	v_mfma_f32_32x32x16_bf16 v[80:95], v[194:197], v[206:209], v[80:95]
	v_mfma_f32_32x32x16_bf16 v[64:79], v[194:197], v[210:213], v[64:79]
	v_mfma_f32_32x32x16_bf16 v[48:63], v[198:201], v[206:209], v[48:63]
	v_mfma_f32_32x32x16_bf16 v[32:47], v[198:201], v[210:213], v[32:47]
	s_setprio 0
	s_xor_b32 s6, s9, 1
	v_mov_b32_e32 v249, v246
	v_mov_b32_e32 v246, v247
	v_mov_b32_e32 v247, v248
	v_mov_b32_e32 v248, v249
	s_waitcnt vmcnt(4)
	s_add_u32 s4, s4, 0x80
	s_addc_u32 s5, s5, 0
	s_cmpk_lg_i32 s4, 0x1f80
	s_waitcnt vmcnt(4)
	s_barrier
	s_cbranch_scc1 .LBB0_226
	v_add_u32_e32 v222, v170, v168
	v_or_b32_e32 v223, v169, v167
	v_lshlrev_b32_e32 v221, 12, v222
	v_lshl_add_u32 v221, v223, 2, v221
	s_add_u32 s0, s68, 0x40000
	s_addc_u32 s1, s69, 0
	global_load_dword v0, v221, s[0:1]
	global_load_dword v16, v221, s[0:1] offset:128
	s_add_u32 s0, s68, 0x41000
	s_addc_u32 s1, s69, 0
	global_load_dword v1, v221, s[0:1]
	global_load_dword v17, v221, s[0:1] offset:128
	s_add_u32 s0, s68, 0x42000
	s_addc_u32 s1, s69, 0
	global_load_dword v2, v221, s[0:1]
	global_load_dword v18, v221, s[0:1] offset:128
	s_add_u32 s0, s68, 0x43000
	s_addc_u32 s1, s69, 0
	global_load_dword v3, v221, s[0:1]
	global_load_dword v19, v221, s[0:1] offset:128
	s_add_u32 s0, s68, 0x48000
	s_addc_u32 s1, s69, 0
	global_load_dword v4, v221, s[0:1]
	global_load_dword v20, v221, s[0:1] offset:128
	s_add_u32 s0, s68, 0x49000
	s_addc_u32 s1, s69, 0
	global_load_dword v5, v221, s[0:1]
	global_load_dword v21, v221, s[0:1] offset:128
	s_add_u32 s0, s68, 0x4a000
	s_addc_u32 s1, s69, 0
	global_load_dword v6, v221, s[0:1]
	global_load_dword v22, v221, s[0:1] offset:128
	s_add_u32 s0, s68, 0x4b000
	s_addc_u32 s1, s69, 0
	global_load_dword v7, v221, s[0:1]
	global_load_dword v23, v221, s[0:1] offset:128
	s_add_u32 s0, s68, 0x50000
	s_addc_u32 s1, s69, 0
	global_load_dword v8, v221, s[0:1]
	global_load_dword v24, v221, s[0:1] offset:128
	s_add_u32 s0, s68, 0x51000
	s_addc_u32 s1, s69, 0
	global_load_dword v9, v221, s[0:1]
	global_load_dword v25, v221, s[0:1] offset:128
	s_add_u32 s0, s68, 0x52000
	s_addc_u32 s1, s69, 0
	global_load_dword v10, v221, s[0:1]
	global_load_dword v26, v221, s[0:1] offset:128
	s_add_u32 s0, s68, 0x53000
	s_addc_u32 s1, s69, 0
	global_load_dword v11, v221, s[0:1]
	global_load_dword v27, v221, s[0:1] offset:128
	s_add_u32 s0, s68, 0x58000
	s_addc_u32 s1, s69, 0
	global_load_dword v12, v221, s[0:1]
	global_load_dword v28, v221, s[0:1] offset:128
	s_add_u32 s0, s68, 0x59000
	s_addc_u32 s1, s69, 0
	global_load_dword v13, v221, s[0:1]
	global_load_dword v29, v221, s[0:1] offset:128
	s_add_u32 s0, s68, 0x5a000
	s_addc_u32 s1, s69, 0
	global_load_dword v14, v221, s[0:1]
	global_load_dword v30, v221, s[0:1] offset:128
	s_add_u32 s0, s68, 0x5b000
	s_addc_u32 s1, s69, 0
	global_load_dword v15, v221, s[0:1]
	global_load_dword v31, v221, s[0:1] offset:128
	v_add_u32_e32 v147, s8, v128
	v_cmp_lt_i32_e64 s[0:1], 31, v147
	s_xor_b64 s[4:5], vcc, -1
	s_nor_b64 s[4:5], s[4:5], s[0:1]
	v_cndmask_b32_e64 v128, v147, v128, s[0:1]
	v_ashrrev_i32_e32 v130, 31, v128
	v_lshrrev_b32_e32 v130, 30, v130
	v_add_u32_e32 v130, v128, v130
	v_lshrrev_b32_e32 v131, 2, v130
	v_and_b32_e32 v130, 0xfffffc, v130
	v_sub_u32_e32 v130, v128, v130
	v_lshlrev_b32_e32 v128, 4, v132
	v_and_b32_e32 v128, 0x70, v128
	v_add_lshl_u32 v146, v131, v166, 8
	v_lshl_add_u64 v[136:137], s[38:39], 0, v[128:129]
	v_lshl_add_u64 v[134:135], s[40:41], 0, v[128:129]
	v_lshlrev_b32_e32 v148, 8, v130
	s_and_saveexec_b64 s[14:15], s[4:5]
	s_xor_b64 s[4:5], exec, s[14:15]
	s_cbranch_execz .LBB0_233
	s_lshl_b32 s7, s6, 16
	s_xor_b32 s13, s7, 0x10000
	v_add_u32_e32 v130, v146, v188
	s_add_i32 s13, s13, 0
	v_ashrrev_i32_e32 v131, 31, v130
	v_add_u32_e32 v132, v187, v146
	v_add_u32_e32 v128, s13, v180
	v_lshlrev_b64 v[130:131], 13, v[130:131]
	v_ashrrev_i32_e32 v133, 31, v132
	v_readfirstlane_b32 s14, v128
	v_add_u32_e32 v142, s13, v179
	v_lshl_add_u64 v[130:131], v[136:137], 0, v[130:131]
	v_lshlrev_b64 v[132:133], 13, v[132:133]
	s_mov_b32 m0, s14
	v_readfirstlane_b32 s14, v142
	v_lshl_add_u64 v[132:133], v[136:137], 0, v[132:133]
	v_add_u32_e32 v138, v186, v146
	global_load_lds_dwordx4 v[130:131], off
	s_mov_b32 m0, s14
	v_ashrrev_i32_e32 v139, 31, v138
	v_add_u32_e32 v140, v185, v146
	global_load_lds_dwordx4 v[132:133], off
	v_add_u32_e32 v132, s13, v178
	v_lshlrev_b64 v[138:139], 13, v[138:139]
	v_ashrrev_i32_e32 v141, 31, v140
	v_readfirstlane_b32 s14, v132
	v_add_u32_e32 v133, s13, v177
	v_add_u32_e32 v130, v148, v188
	v_lshl_add_u64 v[138:139], v[136:137], 0, v[138:139]
	v_lshlrev_b64 v[140:141], 13, v[140:141]
	s_mov_b32 m0, s14
	v_readfirstlane_b32 s13, v133
	v_ashrrev_i32_e32 v131, 31, v130
	v_add_u32_e32 v128, 0x8000, v128
	v_lshl_add_u64 v[140:141], v[136:137], 0, v[140:141]
	global_load_lds_dwordx4 v[138:139], off
	s_mov_b32 m0, s13
	v_lshlrev_b64 v[130:131], 13, v[130:131]
	v_readfirstlane_b32 s13, v128
	global_load_lds_dwordx4 v[140:141], off
	v_lshl_add_u64 v[130:131], v[134:135], 0, v[130:131]
	s_mov_b32 m0, s13
	v_add_u32_e32 v128, 0x8000, v142
	global_load_lds_dwordx4 v[130:131], off
	v_add_u32_e32 v130, v187, v148
	v_ashrrev_i32_e32 v131, 31, v130
	v_lshlrev_b64 v[130:131], 13, v[130:131]
	v_readfirstlane_b32 s13, v128
	v_lshl_add_u64 v[130:131], v[134:135], 0, v[130:131]
	s_mov_b32 m0, s13
	v_add_u32_e32 v128, 0x8000, v132
	global_load_lds_dwordx4 v[130:131], off
	v_add_u32_e32 v130, v186, v148
	v_ashrrev_i32_e32 v131, 31, v130
	v_lshlrev_b64 v[130:131], 13, v[130:131]
	v_readfirstlane_b32 s13, v128
	v_lshl_add_u64 v[130:131], v[134:135], 0, v[130:131]
	s_mov_b32 m0, s13
	v_add_u32_e32 v128, 0x8000, v133
	global_load_lds_dwordx4 v[130:131], off
	v_add_u32_e32 v130, v185, v148
	v_ashrrev_i32_e32 v131, 31, v130
	v_lshlrev_b64 v[130:131], 13, v[130:131]
	v_readfirstlane_b32 s13, v128
	v_lshl_add_u64 v[130:131], v[134:135], 0, v[130:131]
	s_mov_b32 m0, s13
	s_nop 0
	global_load_lds_dwordx4 v[130:131], off
